# selected-branch loop: one static priority raise for the second wave half instead of per-segment priority flips
# baseline (speedup 1.0000x reference)
.LBB0_619:
	s_or_b64 exec, exec, s[0:1]
	v_lshlrev_b32_e32 v29, 5, v111
	v_add_u32_e32 v0, s68, v29
	v_or_b32_e32 v160, v0, v109
	v_or_b32_e32 v156, 16, v160
	v_ashrrev_i32_e32 v161, 31, v160
	v_ashrrev_i32_e32 v157, 31, v156
	v_lshlrev_b64 v[164:165], 12, v[160:161]
	v_lshlrev_b64 v[162:163], 12, v[156:157]
	v_lshl_add_u64 v[12:13], v[82:83], 0, v[164:165]
	v_lshl_add_u64 v[30:31], v[82:83], 0, v[162:163]
	s_waitcnt lgkmcnt(0)
	s_barrier
	flat_load_dwordx4 v[0:3], v[12:13]
	flat_load_dwordx4 v[4:7], v[12:13] offset:64
	flat_load_dwordx4 v[8:11], v[12:13] offset:128
	s_nop 0
	flat_load_dwordx4 v[12:15], v[12:13] offset:192
	s_nop 0
	flat_load_dwordx4 v[16:19], v[30:31]
	flat_load_dwordx4 v[20:23], v[30:31] offset:64
	flat_load_dwordx4 v[24:27], v[30:31] offset:128
	flat_load_dwordx4 v[32:35], v[30:31] offset:192
	v_readlane_b32 s0, v246, 6
	s_lshl_b32 s26, s69, 7
	s_lshl_b32 s27, s69, 20
	v_mov_b32_e32 v30, s0
	ds_read_b32 v30, v30
	s_waitcnt lgkmcnt(0)
	v_cmp_eq_u32_e32 vcc, 0, v30
	v_readfirstlane_b32 s28, v30
	s_cbranch_vccnz .LBB0_679
	v_mov_b32_e32 v52, v154
	v_mov_b32_e32 v30, v155
	v_mov_b32_e32 v31, s50
	ds_read_b32 v31, v31
	s_lshl_b32 s0, s26, 1
	s_add_u32 s12, s43, s0
	s_addc_u32 s13, s42, 0
	s_lshl_b32 s0, s27, 1
	s_add_u32 s14, s45, s0
	s_mov_b32 s0, 0x60000
	s_waitcnt lgkmcnt(0)
	v_mul_hi_i32 v37, v31, s0
	v_mul_lo_u32 v36, v31, s0
	v_lshl_add_u64 v[40:41], s[12:13], 0, v[36:37]
	v_lshlrev_b32_e32 v36, 6, v31
	v_ashrrev_i32_e32 v37, 31, v36
	s_addc_u32 s15, s44, 0
	v_lshlrev_b64 v[36:37], 1, v[36:37]
	v_lshlrev_b32_e32 v31, 3, v52
	v_lshrrev_b32_e32 v53, 4, v52
	s_movk_i32 s0, 0xc00
	v_lshl_add_u64 v[48:49], s[14:15], 0, v[36:37]
	v_and_b32_e32 v42, 0x78, v31
	v_mul_lo_u32 v36, v53, s0
	v_or_b32_e32 v166, v36, v42
	v_mov_b32_e32 v167, v28
	v_lshl_add_u64 v[36:37], v[166:167], 1, v[40:41]
	v_add_u32_e32 v54, 0x200, v52
	global_load_dwordx4 v[36:39], v[36:37], off offset:2048
	v_lshrrev_b32_e32 v55, 4, v54
	v_mul_lo_u32 v43, v55, s0
	v_and_b32_e32 v31, 56, v31
	v_lshlrev_b32_e32 v44, 10, v52
	s_movk_i32 s0, 0xe000
	v_lshlrev_b32_e32 v50, 10, v54
	v_or_b32_e32 v168, v43, v42
	v_mov_b32_e32 v169, v28
	v_and_or_b32 v170, v44, s0, v31
	v_mov_b32_e32 v171, v28
	v_and_or_b32 v172, v50, s0, v31
	v_mov_b32_e32 v173, v28
	v_lshl_add_u64 v[40:41], v[168:169], 1, v[40:41]
	v_lshl_add_u64 v[44:45], v[170:171], 1, v[48:49]
	v_lshl_add_u64 v[48:49], v[172:173], 1, v[48:49]
	global_load_dwordx4 v[40:43], v[40:41], off offset:2048
	v_lshlrev_b32_e32 v56, 4, v52
	global_load_dwordx4 v[44:47], v[44:45], off
	v_and_b32_e32 v31, 0xf0, v56
	global_load_dwordx4 v[48:51], v[48:49], off
	v_add_u32_e32 v57, s54, v31
	v_mul_lo_u32 v157, v53, s83
	v_add_u32_e32 v161, v57, v157
	v_mul_lo_u32 v189, v55, s83
	v_add_u32_e32 v190, v57, v189
	v_readfirstlane_b32 s0, v160
	s_cmp_lt_i32 s28, 1
	s_waitcnt vmcnt(0)
	ds_write_b128 v161, v[36:39]
	v_lshrrev_b32_e32 v38, 3, v52
	v_and_b32_e32 v36, 0x70, v56
	v_mul_lo_u32 v191, v38, s88
	v_lshrrev_b32_e32 v38, 3, v54
	v_add_u32_e32 v37, s79, v36
	v_mul_lo_u32 v193, v38, s88
	v_add_u32_e32 v192, v37, v191
	v_add_u32_e32 v194, v37, v193
	ds_write_b128 v190, v[40:43]
	ds_write_b128 v192, v[44:47]
	ds_write_b128 v194, v[48:51]
	s_waitcnt lgkmcnt(0)
	s_barrier
	s_cbranch_scc1 .LBB0_680
	v_or_b32_e32 v29, v29, v109
	s_add_i32 s1, 0, 0x14440
	v_lshl_add_u32 v195, v29, 4, s1
	v_and_b32_e32 v29, 15, v30
	v_and_b32_e32 v37, -16, v30
	v_ashrrev_i32_e32 v30, 4, v30
	v_lshlrev_b32_e32 v209, 2, v30
	v_lshlrev_b32_e32 v30, 3, v30
	v_add_u32_e32 v38, s54, v37
	v_mul_u32_u24_e32 v39, 0x110, v29
	v_add_u32_e32 v40, s79, v30
	v_mul_u32_u24_e32 v41, 0x90, v29
	v_add_u32_e32 v210, 0, v36
	v_add_u32_e32 v211, 0, v31
	v_add_u32_e32 v36, 0, v37
	v_add_u32_e32 v37, 0, v30
	v_mov_b32_e32 v30, v28
	v_mov_b32_e32 v31, v28
	v_mov_b32_e32 v29, v28
	v_add_u32_e32 v212, v38, v39
	v_add_u32_e32 v213, v40, v41
	v_add_u32_e32 v214, v36, v39
	v_add_u32_e32 v215, v37, v41
	v_mov_b64_e32 v[38:39], v[30:31]
	v_mov_b64_e32 v[42:43], v[30:31]
	v_mov_b64_e32 v[46:47], v[30:31]
	v_mov_b64_e32 v[50:51], v[30:31]
	v_mov_b64_e32 v[54:55], v[30:31]
	v_mov_b64_e32 v[58:59], v[30:31]
	v_mov_b64_e32 v[62:63], v[30:31]
	v_mov_b64_e32 v[66:67], v[30:31]
	v_mov_b64_e32 v[70:71], v[30:31]
	v_mov_b64_e32 v[74:75], v[30:31]
	v_mov_b64_e32 v[78:79], v[30:31]
	v_mov_b64_e32 v[82:83], v[30:31]
	v_mov_b64_e32 v[86:87], v[30:31]
	v_mov_b64_e32 v[90:91], v[30:31]
	v_mov_b64_e32 v[94:95], v[30:31]
	v_mov_b64_e32 v[98:99], v[30:31]
	s_sub_i32 s29, s0, 63
	s_mov_b32 s31, 0
	v_mov_b32_e32 v217, 0xf149f2ca
	v_mov_b32_e32 v117, 0
	v_readlane_b32 s30, v244, 7
	v_mov_b64_e32 v[36:37], v[28:29]
	v_mov_b64_e32 v[40:41], v[28:29]
	v_mov_b64_e32 v[44:45], v[28:29]
	v_mov_b64_e32 v[48:49], v[28:29]
	v_mov_b64_e32 v[52:53], v[28:29]
	v_mov_b64_e32 v[56:57], v[28:29]
	v_mov_b64_e32 v[60:61], v[28:29]
	v_mov_b64_e32 v[64:65], v[28:29]
	v_mov_b64_e32 v[68:69], v[28:29]
	v_mov_b64_e32 v[72:73], v[28:29]
	v_mov_b64_e32 v[76:77], v[28:29]
	v_mov_b64_e32 v[80:81], v[28:29]
	v_mov_b64_e32 v[84:85], v[28:29]
	v_mov_b64_e32 v[88:89], v[28:29]
	v_mov_b64_e32 v[92:93], v[28:29]
	v_mov_b64_e32 v[96:97], v[28:29]
	v_mov_b32_e32 v116, 0
	v_mov_b32_e32 v218, 0xf149f2ca
	v_mov_b32_e32 v216, 0
	v_mov_b32_e32 v29, 0
	ds_read_b32 v239, v151 offset:9728
	s_waitcnt lgkmcnt(0)
	v_readfirstlane_b32 s32, v239
	s_add_i32 s98, s30, -8
	v_mov_b32_e32 v239, s98
	ds_read_b32 v247, v239 offset:4
	ds_read_b32 v239, v239
	s_waitcnt lgkmcnt(0)
	v_readfirstlane_b32 s98, v154
	s_lshr_b32 s98, s98, 8
	s_cmp_eq_u32 s98, 0
	s_cbranch_scc1 .Lb2prio_skip
	s_setprio 1
.Lb2prio_skip:
	s_branch .LBB0_623
.LBB0_622:
	v_mov_b32_e32 v218, v219
	v_mov_b32_e32 v217, v220
	s_mov_b32 s31, s2
	s_add_i32 s30, s30, 8
	s_cmp_lt_i32 s31, s28
	s_cbranch_scc0 .LBB0_681

.LBB0_625:
	s_lshl_b32 s0, 1, s2
	s_waitcnt lgkmcnt(0)
	v_and_b32_e32 v31, s0, v247
	v_and_b32_e32 v30, s0, v239
	v_or_b32_e32 v118, v30, v31
	v_cmp_ne_u32_e64 s[8:9], 0, v31
	v_cmp_ne_u32_e64 s[0:1], 0, v30
	v_cmp_ne_u32_e32 vcc, 0, v118
	s_cbranch_vccz .LBB0_677
	s_lshl_b32 s2, s2, 6
	v_cndmask_b32_e64 v30, 0, 1, s[8:9]
	v_cndmask_b32_e64 v31, 0, 1, s[0:1]
	s_sub_i32 s0, s29, s2
	v_lshlrev_b16_e32 v30, 8, v30
	s_cmpk_lt_i32 s0, 0x80
	v_or_b32_e32 v30, v31, v30
	s_cselect_b64 s[20:21], -1, 0
	s_cmpk_gt_i32 s0, 0x7f
	s_nop 0
	s_waitcnt lgkmcnt(3)
	v_mfma_f32_16x16x32_bf16 v[132:135], v[174:177], v[0:3], 0
	v_mfma_f32_16x16x32_bf16 v[116:119], v[174:177], v[16:19], 0
	ds_read_b128 v[174:177], v212 offset:4352
	s_waitcnt lgkmcnt(3)
	v_mfma_f32_16x16x32_bf16 v[132:135], v[240:243], v[4:7], v[132:135]
	v_mfma_f32_16x16x32_bf16 v[116:119], v[240:243], v[20:23], v[116:119]
	ds_read_b128 v[240:243], v212 offset:4416
	s_waitcnt lgkmcnt(3)
	v_mfma_f32_16x16x32_bf16 v[132:135], v[248:251], v[8:11], v[132:135]
	v_mfma_f32_16x16x32_bf16 v[116:119], v[248:251], v[24:27], v[116:119]
	ds_read_b128 v[248:251], v212 offset:4480
	s_waitcnt lgkmcnt(3)
	v_mfma_f32_16x16x32_bf16 v[132:135], v[252:255], v[12:15], v[132:135]
	v_mfma_f32_16x16x32_bf16 v[116:119], v[252:255], v[32:35], v[116:119]
	ds_read_b128 v[252:255], v212 offset:4544
	s_waitcnt lgkmcnt(3)
	v_mfma_f32_16x16x32_bf16 v[136:139], v[174:177], v[0:3], 0
	v_mfma_f32_16x16x32_bf16 v[120:123], v[174:177], v[16:19], 0
	ds_read_b128 v[174:177], v212 offset:8704
	s_waitcnt lgkmcnt(3)
	v_mfma_f32_16x16x32_bf16 v[136:139], v[240:243], v[4:7], v[136:139]
	v_mfma_f32_16x16x32_bf16 v[120:123], v[240:243], v[20:23], v[120:123]
	ds_read_b128 v[240:243], v212 offset:8768
	s_waitcnt lgkmcnt(3)
	v_mfma_f32_16x16x32_bf16 v[136:139], v[248:251], v[8:11], v[136:139]
	v_mfma_f32_16x16x32_bf16 v[120:123], v[248:251], v[24:27], v[120:123]
	ds_read_b128 v[248:251], v212 offset:8832
	s_waitcnt lgkmcnt(3)
	v_mfma_f32_16x16x32_bf16 v[136:139], v[252:255], v[12:15], v[136:139]
	v_mfma_f32_16x16x32_bf16 v[120:123], v[252:255], v[32:35], v[120:123]
	ds_read_b128 v[252:255], v212 offset:8896
	s_waitcnt lgkmcnt(3)
	v_mfma_f32_16x16x32_bf16 v[140:143], v[174:177], v[0:3], 0
	v_mfma_f32_16x16x32_bf16 v[124:127], v[174:177], v[16:19], 0
	ds_read_b128 v[174:177], v212 offset:13056
	s_waitcnt lgkmcnt(3)
	v_mfma_f32_16x16x32_bf16 v[140:143], v[240:243], v[4:7], v[140:143]
	v_mfma_f32_16x16x32_bf16 v[124:127], v[240:243], v[20:23], v[124:127]
	ds_read_b128 v[240:243], v212 offset:13120
	s_waitcnt lgkmcnt(3)
	v_mfma_f32_16x16x32_bf16 v[140:143], v[248:251], v[8:11], v[140:143]
	v_mfma_f32_16x16x32_bf16 v[124:127], v[248:251], v[24:27], v[124:127]
	ds_read_b128 v[248:251], v212 offset:13184
	s_waitcnt lgkmcnt(3)
	v_mfma_f32_16x16x32_bf16 v[140:143], v[252:255], v[12:15], v[140:143]
	v_mfma_f32_16x16x32_bf16 v[124:127], v[252:255], v[32:35], v[124:127]
	ds_read_b128 v[252:255], v212 offset:13248
	s_waitcnt lgkmcnt(3)
	v_mfma_f32_16x16x32_bf16 v[144:147], v[174:177], v[0:3], 0
	v_mfma_f32_16x16x32_bf16 v[128:131], v[174:177], v[16:19], 0
	s_waitcnt lgkmcnt(2)
	v_mfma_f32_16x16x32_bf16 v[144:147], v[240:243], v[4:7], v[144:147]
	v_mfma_f32_16x16x32_bf16 v[128:131], v[240:243], v[20:23], v[128:131]
	s_waitcnt lgkmcnt(1)
	v_mfma_f32_16x16x32_bf16 v[144:147], v[248:251], v[8:11], v[144:147]
	v_mfma_f32_16x16x32_bf16 v[128:131], v[248:251], v[24:27], v[128:131]
	s_waitcnt lgkmcnt(0)
	v_mfma_f32_16x16x32_bf16 v[144:147], v[252:255], v[12:15], v[144:147]
	v_mfma_f32_16x16x32_bf16 v[128:131], v[252:255], v[32:35], v[128:131]
	s_nop 0
	ds_read2_b64 v[240:243], v213 offset1:4
	v_add_u32_e32 v239, 0x800, v213
	ds_read2_b64 v[248:251], v239 offset0:32 offset1:36
	v_add_u32_e32 v247, 0x1000, v213
	ds_read2_b64 v[252:255], v247 offset0:64 offset1:68
	v_add_u32_e32 v237, s2, v209
	s_mov_b64 s[0:1], -1
	v_and_b32_e32 v238, 1, v30
	v_or_b32_e32 v236, 2, v237
	v_or_b32_e32 v220, 3, v237
	s_cbranch_scc1 .LBB0_628
	v_sub_u32_e32 v179, v160, v237
	v_med3_i32 v30, v179, 0, v207
	v_lshl_add_u32 v30, v30, 2, v151
	ds_read_b32 v30, v30 offset:9216
	v_cmp_lt_i32_e64 s[0:1], -1, v179
	v_cmp_eq_u32_e32 vcc, 1, v238
	s_and_b64 s[0:1], s[0:1], vcc
	v_xad_u32 v31, v237, -1, v160
	s_waitcnt lgkmcnt(0)
	v_add_f32_e32 v30, v132, v30
	v_cndmask_b32_e64 v30, v208, v30, s[0:1]
	v_cmp_lt_i32_e64 s[0:1], -1, v31
	v_med3_i32 v31, v31, 0, v207
	v_lshl_add_u32 v31, v31, 2, v151
	ds_read_b32 v31, v31 offset:9216
	s_and_b64 s[0:1], s[0:1], vcc
	v_sub_u32_e32 v174, v160, v236
	v_sub_u32_e32 v175, v160, v220
	v_subrev_u32_e32 v177, 17, v179
	s_waitcnt lgkmcnt(0)
	v_add_f32_e32 v31, v133, v31
	v_cndmask_b32_e64 v31, v208, v31, s[0:1]
	v_cmp_lt_i32_e64 s[0:1], -1, v174
	v_med3_i32 v174, v174, 0, v207
	v_lshl_add_u32 v174, v174, 2, v151
	ds_read_b32 v174, v174 offset:9216
	s_and_b64 s[0:1], s[0:1], vcc
	v_max3_f32 v176, v30, s82, v31
	v_subrev_u32_e32 v180, 18, v179
	v_subrev_u32_e32 v181, 19, v179
	s_waitcnt lgkmcnt(0)
	v_add_f32_e32 v174, v134, v174
	v_cndmask_b32_e64 v174, v208, v174, s[0:1]
	v_cmp_lt_i32_e64 s[0:1], -1, v175
	v_med3_i32 v175, v175, 0, v207
	v_lshl_add_u32 v175, v175, 2, v151
	ds_read_b32 v175, v175 offset:9216
	s_and_b64 s[0:1], s[0:1], vcc
	v_subrev_u32_e32 v182, 32, v179
	v_subrev_u32_e32 v183, 33, v179
	v_subrev_u32_e32 v184, 34, v179
	s_waitcnt lgkmcnt(0)
	v_add_f32_e32 v175, v135, v175
	v_cndmask_b32_e64 v175, v208, v175, s[0:1]
	v_max3_f32 v178, v176, v174, v175
	v_add_u32_e32 v176, -16, v179
	v_cmp_lt_i32_e64 s[0:1], -1, v176
	v_med3_i32 v176, v176, 0, v207
	v_lshl_add_u32 v176, v176, 2, v151
	ds_read_b32 v176, v176 offset:9216
	s_and_b64 s[0:1], s[0:1], vcc
	v_subrev_u32_e32 v185, 35, v179
	v_subrev_u32_e32 v186, 48, v179
	v_subrev_u32_e32 v187, 49, v179
	s_waitcnt lgkmcnt(0)
	v_add_f32_e32 v176, v136, v176
	v_cndmask_b32_e64 v176, v208, v176, s[0:1]
	v_cmp_lt_i32_e64 s[0:1], -1, v177
	v_med3_i32 v177, v177, 0, v207
	v_lshl_add_u32 v177, v177, 2, v151
	ds_read_b32 v177, v177 offset:9216
	s_and_b64 s[0:1], s[0:1], vcc
	s_waitcnt lgkmcnt(0)
	v_add_f32_e32 v177, v137, v177
	v_cndmask_b32_e64 v177, v208, v177, s[0:1]
	v_cmp_lt_i32_e64 s[0:1], -1, v180
	v_med3_i32 v180, v180, 0, v207
	v_lshl_add_u32 v180, v180, 2, v151
	ds_read_b32 v180, v180 offset:9216
	s_and_b64 s[0:1], s[0:1], vcc
	v_max3_f32 v178, v178, v176, v177
	s_waitcnt lgkmcnt(0)
	v_add_f32_e32 v180, v138, v180
	v_cndmask_b32_e64 v180, v208, v180, s[0:1]
	v_cmp_lt_i32_e64 s[0:1], -1, v181
	s_and_b64 s[10:11], s[0:1], vcc
	v_med3_i32 v181, v181, 0, v207
	v_cmp_lt_i32_e64 s[0:1], -1, v182
	v_med3_i32 v182, v182, 0, v207
	v_lshl_add_u32 v181, v181, 2, v151
	v_lshl_add_u32 v182, v182, 2, v151
	ds_read_b32 v181, v181 offset:9216
	ds_read_b32 v182, v182 offset:9216
	s_and_b64 s[0:1], s[0:1], vcc
	s_waitcnt lgkmcnt(1)
	v_add_f32_e32 v181, v139, v181
	s_waitcnt lgkmcnt(0)
	v_add_f32_e32 v182, v140, v182
	v_cndmask_b32_e64 v182, v208, v182, s[0:1]
	v_cmp_lt_i32_e64 s[0:1], -1, v183
	v_med3_i32 v183, v183, 0, v207
	v_lshl_add_u32 v183, v183, 2, v151
	ds_read_b32 v183, v183 offset:9216
	s_and_b64 s[0:1], s[0:1], vcc
	v_cndmask_b32_e64 v181, v208, v181, s[10:11]
	v_max3_f32 v178, v178, v180, v181
	s_waitcnt lgkmcnt(0)
	v_add_f32_e32 v183, v141, v183
	v_cndmask_b32_e64 v183, v208, v183, s[0:1]
	v_cmp_lt_i32_e64 s[0:1], -1, v184
	v_med3_i32 v184, v184, 0, v207
	v_lshl_add_u32 v184, v184, 2, v151
	ds_read_b32 v184, v184 offset:9216
	s_and_b64 s[0:1], s[0:1], vcc
	v_max3_f32 v178, v178, v182, v183
	s_waitcnt lgkmcnt(0)
	v_add_f32_e32 v184, v142, v184
	v_cndmask_b32_e64 v184, v208, v184, s[0:1]
	v_cmp_lt_i32_e64 s[0:1], -1, v185
	v_med3_i32 v185, v185, 0, v207
	v_lshl_add_u32 v185, v185, 2, v151
	ds_read_b32 v185, v185 offset:9216
	s_and_b64 s[0:1], s[0:1], vcc
	s_waitcnt lgkmcnt(0)
	v_add_f32_e32 v185, v143, v185
	v_cndmask_b32_e64 v185, v208, v185, s[0:1]
	v_cmp_lt_i32_e64 s[0:1], -1, v186
	v_med3_i32 v186, v186, 0, v207
	v_lshl_add_u32 v186, v186, 2, v151
	ds_read_b32 v186, v186 offset:9216
	s_and_b64 s[0:1], s[0:1], vcc
	v_max3_f32 v178, v178, v184, v185
	s_waitcnt lgkmcnt(0)
	v_add_f32_e32 v186, v144, v186
	v_cndmask_b32_e64 v186, v208, v186, s[0:1]
	v_cmp_lt_i32_e64 s[0:1], -1, v187
	v_med3_i32 v187, v187, 0, v207
	v_lshl_add_u32 v187, v187, 2, v151
	ds_read_b32 v187, v187 offset:9216
	s_and_b64 s[0:1], s[0:1], vcc
	s_waitcnt lgkmcnt(0)
	v_add_f32_e32 v187, v145, v187
	v_cndmask_b32_e64 v187, v208, v187, s[0:1]
	v_max3_f32 v219, v178, v186, v187
	v_subrev_u32_e32 v178, 50, v179
	v_cmp_lt_i32_e64 s[0:1], -1, v178
	v_med3_i32 v178, v178, 0, v207
	v_lshl_add_u32 v178, v178, 2, v151
	ds_read_b32 v178, v178 offset:9216
	s_and_b64 s[0:1], s[0:1], vcc
	v_subrev_u32_e32 v179, 51, v179
	s_waitcnt lgkmcnt(0)
	v_add_f32_e32 v178, v146, v178
	v_cndmask_b32_e64 v178, v208, v178, s[0:1]
	v_cmp_lt_i32_e64 s[0:1], -1, v179
	v_med3_i32 v179, v179, 0, v207
	v_lshl_add_u32 v179, v179, 2, v151
	ds_read_b32 v179, v179 offset:9216
	s_and_b64 vcc, s[0:1], vcc
	s_mov_b64 s[0:1], 0
	s_waitcnt lgkmcnt(0)
	v_add_f32_e32 v179, v147, v179
	v_cndmask_b32_e32 v179, v208, v179, vcc
	v_max3_f32 v219, v219, v178, v179

.LBB0_646:
	v_add_f32_e32 v117, v117, v130
	v_fmac_f32_e32 v117, v216, v116
	v_add_f32_e32 v116, v174, v175
	v_fmac_f32_e32 v116, v29, v30
	s_nop 0
	v_cvt_pk_bf16_f32 v130, v221, v222
	v_cvt_pk_bf16_f32 v131, v223, v224
	v_cvt_pk_bf16_f32 v132, v225, v227
	v_cvt_pk_bf16_f32 v133, v229, v231
	v_cvt_pk_bf16_f32 v118, v118, v119
	v_cvt_pk_bf16_f32 v119, v120, v121
	v_cvt_pk_bf16_f32 v120, v122, v124
	v_cvt_pk_bf16_f32 v121, v126, v128
	v_add_u32_e32 v29, 0x800, v213
	v_add_u32_e32 v30, 0x1000, v213
	v_add_u32_e32 v138, 0x1800, v213
	v_add_u32_e32 v139, 0x2000, v213
	v_add_u32_e32 v140, 0x2800, v213
	v_add_u32_e32 v141, 0x3000, v213
	v_add_u32_e32 v142, 0x3800, v213
	ds_read2_b64 v[134:137], v138 offset0:96 offset1:100
	s_waitcnt lgkmcnt(3)
	v_mfma_f32_16x16x32_bf16 v[96:99], v[240:243], v[130:133], v[96:99]
	v_mfma_f32_16x16x32_bf16 v[64:67], v[240:243], v[118:121], v[64:67]
	ds_read2_b64 v[240:243], v139 offset0:128 offset1:132
	s_waitcnt lgkmcnt(3)
	v_mfma_f32_16x16x32_bf16 v[92:95], v[248:251], v[130:133], v[92:95]
	v_mfma_f32_16x16x32_bf16 v[60:63], v[248:251], v[118:121], v[60:63]
	ds_read2_b64 v[248:251], v140 offset0:160 offset1:164
	s_waitcnt lgkmcnt(3)
	v_mfma_f32_16x16x32_bf16 v[88:91], v[252:255], v[130:133], v[88:91]
	v_mfma_f32_16x16x32_bf16 v[56:59], v[252:255], v[118:121], v[56:59]
	ds_read2_b64 v[252:255], v141 offset0:192 offset1:196
	s_waitcnt lgkmcnt(3)
	v_mfma_f32_16x16x32_bf16 v[84:87], v[134:137], v[130:133], v[84:87]
	v_mfma_f32_16x16x32_bf16 v[52:55], v[134:137], v[118:121], v[52:55]
	ds_read2_b64 v[134:137], v142 offset0:224 offset1:228
	s_waitcnt lgkmcnt(3)
	v_mfma_f32_16x16x32_bf16 v[80:83], v[240:243], v[130:133], v[80:83]
	v_mfma_f32_16x16x32_bf16 v[48:51], v[240:243], v[118:121], v[48:51]
	ds_read2_b64 v[240:243], v213 offset0:8 offset1:12
	s_waitcnt lgkmcnt(3)
	v_mfma_f32_16x16x32_bf16 v[76:79], v[248:251], v[130:133], v[76:79]
	v_mfma_f32_16x16x32_bf16 v[44:47], v[248:251], v[118:121], v[44:47]
	ds_read2_b64 v[248:251], v29 offset0:40 offset1:44
	s_waitcnt lgkmcnt(3)
	v_mfma_f32_16x16x32_bf16 v[72:75], v[252:255], v[130:133], v[72:75]
	v_mfma_f32_16x16x32_bf16 v[40:43], v[252:255], v[118:121], v[40:43]
	ds_read2_b64 v[252:255], v30 offset0:72 offset1:76
	s_waitcnt lgkmcnt(3)
	v_mfma_f32_16x16x32_bf16 v[36:39], v[134:137], v[118:121], v[36:39]
	v_mfma_f32_16x16x32_bf16 v[68:71], v[134:137], v[130:133], v[68:71]
	ds_read2_b64 v[134:137], v138 offset0:104 offset1:108
	v_cvt_pk_bf16_f32 v118, v226, v228
	v_cvt_pk_bf16_f32 v119, v230, v232
	v_cvt_pk_bf16_f32 v120, v233, v234
	v_cvt_pk_bf16_f32 v121, v235, v31
	v_cvt_pk_bf16_f32 v122, v123, v125
	v_cvt_pk_bf16_f32 v123, v127, v176
	v_cvt_pk_bf16_f32 v124, v187, v218
	v_cvt_pk_bf16_f32 v125, v236, v129
	s_nop 1
	s_waitcnt lgkmcnt(3)
	v_mfma_f32_16x16x32_bf16 v[96:99], v[240:243], v[118:121], v[96:99]
	v_mfma_f32_16x16x32_bf16 v[64:67], v[240:243], v[122:125], v[64:67]
	ds_read2_b64 v[240:243], v139 offset0:136 offset1:140
	s_waitcnt lgkmcnt(3)
	v_mfma_f32_16x16x32_bf16 v[92:95], v[248:251], v[118:121], v[92:95]
	v_mfma_f32_16x16x32_bf16 v[60:63], v[248:251], v[122:125], v[60:63]
	ds_read2_b64 v[248:251], v140 offset0:168 offset1:172
	s_waitcnt lgkmcnt(3)
	v_mfma_f32_16x16x32_bf16 v[88:91], v[252:255], v[118:121], v[88:91]
	v_mfma_f32_16x16x32_bf16 v[56:59], v[252:255], v[122:125], v[56:59]
	ds_read2_b64 v[252:255], v141 offset0:200 offset1:204
	s_waitcnt lgkmcnt(3)
	v_mfma_f32_16x16x32_bf16 v[84:87], v[134:137], v[118:121], v[84:87]
	v_mfma_f32_16x16x32_bf16 v[52:55], v[134:137], v[122:125], v[52:55]
	ds_read2_b64 v[134:137], v142 offset0:232 offset1:236
	s_waitcnt lgkmcnt(3)
	v_mfma_f32_16x16x32_bf16 v[80:83], v[240:243], v[118:121], v[80:83]
	v_mfma_f32_16x16x32_bf16 v[48:51], v[240:243], v[122:125], v[48:51]
	s_waitcnt lgkmcnt(2)
	v_mfma_f32_16x16x32_bf16 v[76:79], v[248:251], v[118:121], v[76:79]
	v_mfma_f32_16x16x32_bf16 v[44:47], v[248:251], v[122:125], v[44:47]
	s_waitcnt lgkmcnt(1)
	v_mfma_f32_16x16x32_bf16 v[72:75], v[252:255], v[118:121], v[72:75]
	v_mfma_f32_16x16x32_bf16 v[40:43], v[252:255], v[122:125], v[40:43]
	s_waitcnt lgkmcnt(0)
	v_mfma_f32_16x16x32_bf16 v[68:71], v[134:137], v[118:121], v[68:71]
	v_mfma_f32_16x16x32_bf16 v[36:39], v[134:137], v[122:125], v[36:39]
	s_nop 0
	v_mov_b32_e32 v29, v116
	v_mov_b32_e32 v216, v117
	s_andn2_b64 vcc, exec, s[18:19]
	s_cbranch_vccnz .LBB0_648

.LBB0_653:
	s_lshl_b32 s0, 1, s2
	s_waitcnt lgkmcnt(0)
	v_and_b32_e32 v31, s0, v247
	v_and_b32_e32 v30, s0, v239
	v_or_b32_e32 v118, v30, v31
	v_cmp_ne_u32_e64 s[8:9], 0, v31
	v_cmp_ne_u32_e64 s[0:1], 0, v30
	v_cmp_ne_u32_e32 vcc, 0, v118
	s_cbranch_vccz .LBB0_678
	s_lshl_b32 s2, s2, 6
	v_cndmask_b32_e64 v30, 0, 1, s[8:9]
	v_cndmask_b32_e64 v31, 0, 1, s[0:1]
	s_sub_i32 s0, s29, s2
	v_lshlrev_b16_e32 v30, 8, v30
	s_cmpk_lt_i32 s0, 0x80
	v_or_b32_e32 v30, v31, v30
	s_cselect_b64 s[18:19], -1, 0
	s_cmpk_gt_i32 s0, 0x7f
	s_nop 0
	s_waitcnt lgkmcnt(3)
	v_mfma_f32_16x16x32_bf16 v[132:135], v[174:177], v[0:3], 0
	v_mfma_f32_16x16x32_bf16 v[116:119], v[174:177], v[16:19], 0
	ds_read_b128 v[174:177], v214 offset:15680
	s_waitcnt lgkmcnt(3)
	v_mfma_f32_16x16x32_bf16 v[132:135], v[240:243], v[4:7], v[132:135]
	v_mfma_f32_16x16x32_bf16 v[116:119], v[240:243], v[20:23], v[116:119]
	ds_read_b128 v[240:243], v214 offset:15744
	s_waitcnt lgkmcnt(3)
	v_mfma_f32_16x16x32_bf16 v[132:135], v[248:251], v[8:11], v[132:135]
	v_mfma_f32_16x16x32_bf16 v[116:119], v[248:251], v[24:27], v[116:119]
	ds_read_b128 v[248:251], v214 offset:15808
	s_waitcnt lgkmcnt(3)
	v_mfma_f32_16x16x32_bf16 v[132:135], v[252:255], v[12:15], v[132:135]
	v_mfma_f32_16x16x32_bf16 v[116:119], v[252:255], v[32:35], v[116:119]
	ds_read_b128 v[252:255], v214 offset:15872
	s_waitcnt lgkmcnt(3)
	v_mfma_f32_16x16x32_bf16 v[136:139], v[174:177], v[0:3], 0
	v_mfma_f32_16x16x32_bf16 v[120:123], v[174:177], v[16:19], 0
	ds_read_b128 v[174:177], v214 offset:20032
	s_waitcnt lgkmcnt(3)
	v_mfma_f32_16x16x32_bf16 v[136:139], v[240:243], v[4:7], v[136:139]
	v_mfma_f32_16x16x32_bf16 v[120:123], v[240:243], v[20:23], v[120:123]
	ds_read_b128 v[240:243], v214 offset:20096
	s_waitcnt lgkmcnt(3)
	v_mfma_f32_16x16x32_bf16 v[136:139], v[248:251], v[8:11], v[136:139]
	v_mfma_f32_16x16x32_bf16 v[120:123], v[248:251], v[24:27], v[120:123]
	ds_read_b128 v[248:251], v214 offset:20160
	s_waitcnt lgkmcnt(3)
	v_mfma_f32_16x16x32_bf16 v[136:139], v[252:255], v[12:15], v[136:139]
	v_mfma_f32_16x16x32_bf16 v[120:123], v[252:255], v[32:35], v[120:123]
	ds_read_b128 v[252:255], v214 offset:20224
	s_waitcnt lgkmcnt(3)
	v_mfma_f32_16x16x32_bf16 v[140:143], v[174:177], v[0:3], 0
	v_mfma_f32_16x16x32_bf16 v[124:127], v[174:177], v[16:19], 0
	ds_read_b128 v[174:177], v214 offset:24384
	s_waitcnt lgkmcnt(3)
	v_mfma_f32_16x16x32_bf16 v[140:143], v[240:243], v[4:7], v[140:143]
	v_mfma_f32_16x16x32_bf16 v[124:127], v[240:243], v[20:23], v[124:127]
	ds_read_b128 v[240:243], v214 offset:24448
	s_waitcnt lgkmcnt(3)
	v_mfma_f32_16x16x32_bf16 v[140:143], v[248:251], v[8:11], v[140:143]
	v_mfma_f32_16x16x32_bf16 v[124:127], v[248:251], v[24:27], v[124:127]
	ds_read_b128 v[248:251], v214 offset:24512
	s_waitcnt lgkmcnt(3)
	v_mfma_f32_16x16x32_bf16 v[140:143], v[252:255], v[12:15], v[140:143]
	v_mfma_f32_16x16x32_bf16 v[124:127], v[252:255], v[32:35], v[124:127]
	ds_read_b128 v[252:255], v214 offset:24576
	s_waitcnt lgkmcnt(3)
	v_mfma_f32_16x16x32_bf16 v[144:147], v[174:177], v[0:3], 0
	v_mfma_f32_16x16x32_bf16 v[128:131], v[174:177], v[16:19], 0
	s_waitcnt lgkmcnt(2)
	v_mfma_f32_16x16x32_bf16 v[144:147], v[240:243], v[4:7], v[144:147]
	v_mfma_f32_16x16x32_bf16 v[128:131], v[240:243], v[20:23], v[128:131]
	s_waitcnt lgkmcnt(1)
	v_mfma_f32_16x16x32_bf16 v[144:147], v[248:251], v[8:11], v[144:147]
	v_mfma_f32_16x16x32_bf16 v[128:131], v[248:251], v[24:27], v[128:131]
	s_waitcnt lgkmcnt(0)
	v_mfma_f32_16x16x32_bf16 v[144:147], v[252:255], v[12:15], v[144:147]
	v_mfma_f32_16x16x32_bf16 v[128:131], v[252:255], v[32:35], v[128:131]
	s_nop 0
	v_add_u32_e32 v239, 0x7000, v215
	ds_read2_b64 v[240:243], v239 offset0:8 offset1:12
	v_add_u32_e32 v247, 0x7800, v215
	ds_read2_b64 v[248:251], v247 offset0:40 offset1:44
	v_add_u32_e32 v237, s2, v209
	s_mov_b64 s[0:1], -1
	v_and_b32_e32 v238, 1, v30
	v_or_b32_e32 v236, 2, v237
	v_or_b32_e32 v217, 3, v237
	s_cbranch_scc1 .LBB0_656
	v_sub_u32_e32 v179, v160, v237
	v_med3_i32 v30, v179, 0, v207
	v_lshl_add_u32 v30, v30, 2, v151
	ds_read_b32 v30, v30 offset:9216
	v_cmp_lt_i32_e64 s[0:1], -1, v179
	v_cmp_eq_u32_e32 vcc, 1, v238
	s_and_b64 s[0:1], s[0:1], vcc
	v_xad_u32 v31, v237, -1, v160
	s_waitcnt lgkmcnt(0)
	v_add_f32_e32 v30, v132, v30
	v_cndmask_b32_e64 v30, v208, v30, s[0:1]
	v_cmp_lt_i32_e64 s[0:1], -1, v31
	v_med3_i32 v31, v31, 0, v207
	v_lshl_add_u32 v31, v31, 2, v151
	ds_read_b32 v31, v31 offset:9216
	s_and_b64 s[0:1], s[0:1], vcc
	v_sub_u32_e32 v174, v160, v236
	v_sub_u32_e32 v175, v160, v217
	v_subrev_u32_e32 v177, 17, v179
	s_waitcnt lgkmcnt(0)
	v_add_f32_e32 v31, v133, v31
	v_cndmask_b32_e64 v31, v208, v31, s[0:1]
	v_cmp_lt_i32_e64 s[0:1], -1, v174
	v_med3_i32 v174, v174, 0, v207
	v_lshl_add_u32 v174, v174, 2, v151
	ds_read_b32 v174, v174 offset:9216
	s_and_b64 s[0:1], s[0:1], vcc
	v_max3_f32 v176, v30, s82, v31
	v_subrev_u32_e32 v180, 18, v179
	v_subrev_u32_e32 v181, 19, v179
	s_waitcnt lgkmcnt(0)
	v_add_f32_e32 v174, v134, v174
	v_cndmask_b32_e64 v174, v208, v174, s[0:1]
	v_cmp_lt_i32_e64 s[0:1], -1, v175
	v_med3_i32 v175, v175, 0, v207
	v_lshl_add_u32 v175, v175, 2, v151
	ds_read_b32 v175, v175 offset:9216
	s_and_b64 s[0:1], s[0:1], vcc
	v_subrev_u32_e32 v182, 32, v179
	v_subrev_u32_e32 v183, 33, v179
	v_subrev_u32_e32 v184, 34, v179
	s_waitcnt lgkmcnt(0)
	v_add_f32_e32 v175, v135, v175
	v_cndmask_b32_e64 v175, v208, v175, s[0:1]
	v_max3_f32 v178, v176, v174, v175
	v_add_u32_e32 v176, -16, v179
	v_cmp_lt_i32_e64 s[0:1], -1, v176
	v_med3_i32 v176, v176, 0, v207
	v_lshl_add_u32 v176, v176, 2, v151
	ds_read_b32 v176, v176 offset:9216
	s_and_b64 s[0:1], s[0:1], vcc
	v_subrev_u32_e32 v185, 35, v179
	v_subrev_u32_e32 v186, 48, v179
	v_subrev_u32_e32 v187, 49, v179
	s_waitcnt lgkmcnt(0)
	v_add_f32_e32 v176, v136, v176
	v_cndmask_b32_e64 v176, v208, v176, s[0:1]
	v_cmp_lt_i32_e64 s[0:1], -1, v177
	v_med3_i32 v177, v177, 0, v207
	v_lshl_add_u32 v177, v177, 2, v151
	ds_read_b32 v177, v177 offset:9216
	s_and_b64 s[0:1], s[0:1], vcc
	s_waitcnt lgkmcnt(0)
	v_add_f32_e32 v177, v137, v177
	v_cndmask_b32_e64 v177, v208, v177, s[0:1]
	v_cmp_lt_i32_e64 s[0:1], -1, v180
	v_med3_i32 v180, v180, 0, v207
	v_lshl_add_u32 v180, v180, 2, v151
	ds_read_b32 v180, v180 offset:9216
	s_and_b64 s[0:1], s[0:1], vcc
	v_max3_f32 v178, v178, v176, v177
	s_waitcnt lgkmcnt(0)
	v_add_f32_e32 v180, v138, v180
	v_cndmask_b32_e64 v180, v208, v180, s[0:1]
	v_cmp_lt_i32_e64 s[0:1], -1, v181
	s_and_b64 s[10:11], s[0:1], vcc
	v_med3_i32 v181, v181, 0, v207
	v_cmp_lt_i32_e64 s[0:1], -1, v182
	v_med3_i32 v182, v182, 0, v207
	v_lshl_add_u32 v181, v181, 2, v151
	v_lshl_add_u32 v182, v182, 2, v151
	ds_read_b32 v181, v181 offset:9216
	ds_read_b32 v182, v182 offset:9216
	s_and_b64 s[0:1], s[0:1], vcc
	s_waitcnt lgkmcnt(1)
	v_add_f32_e32 v181, v139, v181
	s_waitcnt lgkmcnt(0)
	v_add_f32_e32 v182, v140, v182
	v_cndmask_b32_e64 v182, v208, v182, s[0:1]
	v_cmp_lt_i32_e64 s[0:1], -1, v183
	v_med3_i32 v183, v183, 0, v207
	v_lshl_add_u32 v183, v183, 2, v151
	ds_read_b32 v183, v183 offset:9216
	s_and_b64 s[0:1], s[0:1], vcc
	v_cndmask_b32_e64 v181, v208, v181, s[10:11]
	v_max3_f32 v178, v178, v180, v181
	s_waitcnt lgkmcnt(0)
	v_add_f32_e32 v183, v141, v183
	v_cndmask_b32_e64 v183, v208, v183, s[0:1]
	v_cmp_lt_i32_e64 s[0:1], -1, v184
	v_med3_i32 v184, v184, 0, v207
	v_lshl_add_u32 v184, v184, 2, v151
	ds_read_b32 v184, v184 offset:9216
	s_and_b64 s[0:1], s[0:1], vcc
	v_max3_f32 v178, v178, v182, v183
	s_waitcnt lgkmcnt(0)
	v_add_f32_e32 v184, v142, v184
	v_cndmask_b32_e64 v184, v208, v184, s[0:1]
	v_cmp_lt_i32_e64 s[0:1], -1, v185
	v_med3_i32 v185, v185, 0, v207
	v_lshl_add_u32 v185, v185, 2, v151
	ds_read_b32 v185, v185 offset:9216
	s_and_b64 s[0:1], s[0:1], vcc
	s_waitcnt lgkmcnt(0)
	v_add_f32_e32 v185, v143, v185
	v_cndmask_b32_e64 v185, v208, v185, s[0:1]
	v_cmp_lt_i32_e64 s[0:1], -1, v186
	v_med3_i32 v186, v186, 0, v207
	v_lshl_add_u32 v186, v186, 2, v151
	ds_read_b32 v186, v186 offset:9216
	s_and_b64 s[0:1], s[0:1], vcc
	v_max3_f32 v178, v178, v184, v185
	s_waitcnt lgkmcnt(0)
	v_add_f32_e32 v186, v144, v186
	v_cndmask_b32_e64 v186, v208, v186, s[0:1]
	v_cmp_lt_i32_e64 s[0:1], -1, v187
	v_med3_i32 v187, v187, 0, v207
	v_lshl_add_u32 v187, v187, 2, v151
	ds_read_b32 v187, v187 offset:9216
	s_and_b64 s[0:1], s[0:1], vcc
	s_waitcnt lgkmcnt(0)
	v_add_f32_e32 v187, v145, v187
	v_cndmask_b32_e64 v187, v208, v187, s[0:1]
	v_max3_f32 v218, v178, v186, v187
	v_subrev_u32_e32 v178, 50, v179
	v_cmp_lt_i32_e64 s[0:1], -1, v178
	v_med3_i32 v178, v178, 0, v207
	v_lshl_add_u32 v178, v178, 2, v151
	ds_read_b32 v178, v178 offset:9216
	s_and_b64 s[0:1], s[0:1], vcc
	v_subrev_u32_e32 v179, 51, v179
	s_waitcnt lgkmcnt(0)
	v_add_f32_e32 v178, v146, v178
	v_cndmask_b32_e64 v178, v208, v178, s[0:1]
	v_cmp_lt_i32_e64 s[0:1], -1, v179
	v_med3_i32 v179, v179, 0, v207
	v_lshl_add_u32 v179, v179, 2, v151
	ds_read_b32 v179, v179 offset:9216
	s_and_b64 vcc, s[0:1], vcc
	s_mov_b64 s[0:1], 0
	s_waitcnt lgkmcnt(0)
	v_add_f32_e32 v179, v147, v179
	v_cndmask_b32_e32 v179, v208, v179, vcc
	v_max3_f32 v218, v218, v178, v179

.LBB0_674:
	v_add_f32_e32 v117, v117, v130
	v_fmac_f32_e32 v117, v216, v116
	v_add_f32_e32 v116, v174, v175
	v_fmac_f32_e32 v116, v29, v30
	s_nop 0
	v_cvt_pk_bf16_f32 v132, v221, v222
	v_cvt_pk_bf16_f32 v133, v223, v224
	v_cvt_pk_bf16_f32 v134, v225, v227
	v_cvt_pk_bf16_f32 v135, v229, v231
	v_cvt_pk_bf16_f32 v118, v118, v119
	v_cvt_pk_bf16_f32 v119, v120, v121
	v_cvt_pk_bf16_f32 v120, v122, v124
	v_cvt_pk_bf16_f32 v121, v126, v128
	v_add_u32_e32 v29, 0x7000, v215
	v_add_u32_e32 v30, 0x7800, v215
	v_add_u32_e32 v130, 0x8000, v215
	v_add_u32_e32 v140, 0x8800, v215
	v_add_u32_e32 v141, 0x9000, v215
	v_add_u32_e32 v142, 0x9800, v215
	v_add_u32_e32 v143, 0xa000, v215
	v_add_u32_e32 v144, 0xa800, v215
	ds_read2_b64 v[252:255], v130 offset0:72 offset1:76
	ds_read2_b64 v[136:139], v140 offset0:104 offset1:108
	s_waitcnt lgkmcnt(3)
	v_mfma_f32_16x16x32_bf16 v[96:99], v[240:243], v[132:135], v[96:99]
	v_mfma_f32_16x16x32_bf16 v[64:67], v[240:243], v[118:121], v[64:67]
	ds_read2_b64 v[240:243], v141 offset0:136 offset1:140
	s_waitcnt lgkmcnt(3)
	v_mfma_f32_16x16x32_bf16 v[92:95], v[248:251], v[132:135], v[92:95]
	v_mfma_f32_16x16x32_bf16 v[60:63], v[248:251], v[118:121], v[60:63]
	ds_read2_b64 v[248:251], v142 offset0:168 offset1:172
	s_waitcnt lgkmcnt(3)
	v_mfma_f32_16x16x32_bf16 v[88:91], v[252:255], v[132:135], v[88:91]
	v_mfma_f32_16x16x32_bf16 v[56:59], v[252:255], v[118:121], v[56:59]
	ds_read2_b64 v[252:255], v143 offset0:200 offset1:204
	s_waitcnt lgkmcnt(3)
	v_mfma_f32_16x16x32_bf16 v[84:87], v[136:139], v[132:135], v[84:87]
	v_mfma_f32_16x16x32_bf16 v[52:55], v[136:139], v[118:121], v[52:55]
	ds_read2_b64 v[136:139], v144 offset0:232 offset1:236
	s_waitcnt lgkmcnt(3)
	v_mfma_f32_16x16x32_bf16 v[80:83], v[240:243], v[132:135], v[80:83]
	v_mfma_f32_16x16x32_bf16 v[48:51], v[240:243], v[118:121], v[48:51]
	ds_read2_b64 v[240:243], v29 offset0:16 offset1:20
	s_waitcnt lgkmcnt(3)
	v_mfma_f32_16x16x32_bf16 v[76:79], v[248:251], v[132:135], v[76:79]
	v_mfma_f32_16x16x32_bf16 v[44:47], v[248:251], v[118:121], v[44:47]
	ds_read2_b64 v[248:251], v30 offset0:48 offset1:52
	s_waitcnt lgkmcnt(3)
	v_mfma_f32_16x16x32_bf16 v[72:75], v[252:255], v[132:135], v[72:75]
	v_mfma_f32_16x16x32_bf16 v[40:43], v[252:255], v[118:121], v[40:43]
	ds_read2_b64 v[252:255], v130 offset0:80 offset1:84
	s_waitcnt lgkmcnt(3)
	v_mfma_f32_16x16x32_bf16 v[36:39], v[136:139], v[118:121], v[36:39]
	v_mfma_f32_16x16x32_bf16 v[68:71], v[136:139], v[132:135], v[68:71]
	ds_read2_b64 v[136:139], v140 offset0:112 offset1:116
	v_cvt_pk_bf16_f32 v118, v226, v228
	v_cvt_pk_bf16_f32 v119, v230, v232
	v_cvt_pk_bf16_f32 v120, v233, v234
	v_cvt_pk_bf16_f32 v121, v235, v31
	v_cvt_pk_bf16_f32 v122, v123, v125
	v_cvt_pk_bf16_f32 v123, v127, v131
	v_cvt_pk_bf16_f32 v124, v187, v219
	v_cvt_pk_bf16_f32 v125, v236, v129
	s_nop 1
	s_waitcnt lgkmcnt(3)
	v_mfma_f32_16x16x32_bf16 v[96:99], v[240:243], v[118:121], v[96:99]
	v_mfma_f32_16x16x32_bf16 v[64:67], v[240:243], v[122:125], v[64:67]
	ds_read2_b64 v[240:243], v141 offset0:144 offset1:148
	s_waitcnt lgkmcnt(3)
	v_mfma_f32_16x16x32_bf16 v[92:95], v[248:251], v[118:121], v[92:95]
	v_mfma_f32_16x16x32_bf16 v[60:63], v[248:251], v[122:125], v[60:63]
	ds_read2_b64 v[248:251], v142 offset0:176 offset1:180
	s_waitcnt lgkmcnt(3)
	v_mfma_f32_16x16x32_bf16 v[88:91], v[252:255], v[118:121], v[88:91]
	v_mfma_f32_16x16x32_bf16 v[56:59], v[252:255], v[122:125], v[56:59]
	ds_read2_b64 v[252:255], v143 offset0:208 offset1:212
	s_waitcnt lgkmcnt(3)
	v_mfma_f32_16x16x32_bf16 v[84:87], v[136:139], v[118:121], v[84:87]
	v_mfma_f32_16x16x32_bf16 v[52:55], v[136:139], v[122:125], v[52:55]
	ds_read2_b64 v[136:139], v144 offset0:240 offset1:244
	s_waitcnt lgkmcnt(3)
	v_mfma_f32_16x16x32_bf16 v[80:83], v[240:243], v[118:121], v[80:83]
	v_mfma_f32_16x16x32_bf16 v[48:51], v[240:243], v[122:125], v[48:51]
	s_waitcnt lgkmcnt(2)
	v_mfma_f32_16x16x32_bf16 v[76:79], v[248:251], v[118:121], v[76:79]
	v_mfma_f32_16x16x32_bf16 v[44:47], v[248:251], v[122:125], v[44:47]
	s_waitcnt lgkmcnt(1)
	v_mfma_f32_16x16x32_bf16 v[72:75], v[252:255], v[118:121], v[72:75]
	v_mfma_f32_16x16x32_bf16 v[40:43], v[252:255], v[122:125], v[40:43]
	s_waitcnt lgkmcnt(0)
	v_mfma_f32_16x16x32_bf16 v[68:71], v[136:139], v[118:121], v[68:71]
	v_mfma_f32_16x16x32_bf16 v[36:39], v[136:139], v[122:125], v[36:39]
	s_nop 0
	v_mov_b32_e32 v29, v116
	v_mov_b32_e32 v216, v117
	s_andn2_b64 vcc, exec, s[16:17]
	s_cbranch_vccnz .LBB0_676

.LBB0_681:
	s_setprio 0
	v_mov_b32_e32 v30, 0
	v_cmp_lt_f32_e32 vcc, 0, v116
	s_waitcnt vmcnt(0)
	v_mov_b32_e32 v100, 0
	s_and_saveexec_b64 s[0:1], vcc
	s_cbranch_execz .LBB0_683
	v_mad_i64_i32 v[100:101], s[2:3], v160, s84, v[152:153]
	flat_load_dword v29, v[100:101] offset:4
	s_waitcnt vmcnt(0) lgkmcnt(0)
	v_div_scale_f32 v31, s[2:3], v116, v116, v29
	v_rcp_f32_e32 v100, v31
	v_div_scale_f32 v101, vcc, v29, v116, v29
	v_fma_f32 v102, -v31, v100, 1.0
	v_fmac_f32_e32 v100, v102, v100
	v_mul_f32_e32 v102, v101, v100
	v_fma_f32 v103, -v31, v102, v101
	v_fmac_f32_e32 v102, v103, v100
	v_fma_f32 v31, -v31, v102, v101
	v_div_fmas_f32 v31, v31, v100, v102
	v_div_fixup_f32 v100, v31, v116, v29
